# v17 + phase_mod: all 16 weight-row loads of an item in flight (k-loop unrolled, counted vmcnt) instead of 4 serialised round trips
# baseline (speedup 1.0000x reference)
.LBB0_19:
	v_lshl_add_u64 v[222:223], v[26:27], 0, s[12:13]
	global_load_dwordx4 v[154:157], v[222:223], off nt
	s_add_u32 s12, s12, 0x6000
	s_addc_u32 s13, s13, 0
	v_lshl_add_u64 v[224:225], v[26:27], 0, s[12:13]
	global_load_dwordx4 v[158:161], v[224:225], off nt
	s_add_u32 s12, s12, 0x6000
	s_addc_u32 s13, s13, 0
	v_lshl_add_u64 v[226:227], v[26:27], 0, s[12:13]
	global_load_dwordx4 v[162:165], v[226:227], off nt
	s_add_u32 s12, s12, 0x6000
	s_addc_u32 s13, s13, 0
	v_lshl_add_u64 v[228:229], v[26:27], 0, s[12:13]
	global_load_dwordx4 v[166:169], v[228:229], off nt
	s_add_u32 s12, s12, 0x6000
	s_addc_u32 s13, s13, 0
	v_lshl_add_u64 v[222:223], v[26:27], 0, s[12:13]
	global_load_dwordx4 v[170:173], v[222:223], off nt
	s_add_u32 s12, s12, 0x6000
	s_addc_u32 s13, s13, 0
	v_lshl_add_u64 v[224:225], v[26:27], 0, s[12:13]
	global_load_dwordx4 v[174:177], v[224:225], off nt
	s_add_u32 s12, s12, 0x6000
	s_addc_u32 s13, s13, 0
	v_lshl_add_u64 v[226:227], v[26:27], 0, s[12:13]
	global_load_dwordx4 v[178:181], v[226:227], off nt
	s_add_u32 s12, s12, 0x6000
	s_addc_u32 s13, s13, 0
	v_lshl_add_u64 v[228:229], v[26:27], 0, s[12:13]
	global_load_dwordx4 v[182:185], v[228:229], off nt
	s_add_u32 s12, s12, 0x6000
	s_addc_u32 s13, s13, 0
	v_lshl_add_u64 v[222:223], v[26:27], 0, s[12:13]
	global_load_dwordx4 v[186:189], v[222:223], off nt
	s_add_u32 s12, s12, 0x6000
	s_addc_u32 s13, s13, 0
	v_lshl_add_u64 v[224:225], v[26:27], 0, s[12:13]
	global_load_dwordx4 v[190:193], v[224:225], off nt
	s_add_u32 s12, s12, 0x6000
	s_addc_u32 s13, s13, 0
	v_lshl_add_u64 v[226:227], v[26:27], 0, s[12:13]
	global_load_dwordx4 v[194:197], v[226:227], off nt
	s_add_u32 s12, s12, 0x6000
	s_addc_u32 s13, s13, 0
	v_lshl_add_u64 v[228:229], v[26:27], 0, s[12:13]
	global_load_dwordx4 v[198:201], v[228:229], off nt
	s_add_u32 s12, s12, 0x6000
	s_addc_u32 s13, s13, 0
	v_lshl_add_u64 v[222:223], v[26:27], 0, s[12:13]
	global_load_dwordx4 v[206:209], v[222:223], off nt
	s_add_u32 s12, s12, 0x6000
	s_addc_u32 s13, s13, 0
	v_lshl_add_u64 v[224:225], v[26:27], 0, s[12:13]
	global_load_dwordx4 v[210:213], v[224:225], off nt
	s_add_u32 s12, s12, 0x6000
	s_addc_u32 s13, s13, 0
	v_lshl_add_u64 v[226:227], v[26:27], 0, s[12:13]
	global_load_dwordx4 v[214:217], v[226:227], off nt
	s_add_u32 s12, s12, 0x6000
	s_addc_u32 s13, s13, 0
	v_lshl_add_u64 v[228:229], v[26:27], 0, s[12:13]
	global_load_dwordx4 v[218:221], v[228:229], off nt
	s_add_u32 s12, s12, 0x6000
	s_addc_u32 s13, s13, 0
	ds_read_b128 v[48:51], v31
	ds_read_b128 v[52:55], v31 offset:4096
	ds_read_b128 v[56:59], v31 offset:8192
	ds_read_b128 v[60:63], v31 offset:12288
	ds_read_b128 v[64:67], v31 offset:16384
	s_waitcnt lgkmcnt(4)
	v_mov_b32_e32 v68, v51
	s_waitcnt lgkmcnt(3)
	v_mov_b32_e32 v70, v55
	s_waitcnt lgkmcnt(2)
	v_mov_b32_e32 v72, v59
	s_waitcnt lgkmcnt(1)
	v_mov_b32_e32 v74, v63
	s_waitcnt lgkmcnt(0)
	v_mov_b32_e32 v76, v67
	v_add_u32_e32 v31, 16, v31
	s_waitcnt vmcnt(15)
	v_pk_fma_f32 v[6:7], v[48:49], v[154:155], v[6:7] op_sel_hi:[0,1,1]
	v_pk_fma_f32 v[8:9], v[48:49], v[156:157], v[8:9] op_sel_hi:[0,1,1]
	v_pk_fma_f32 v[18:19], v[154:155], v[52:53], v[18:19] op_sel_hi:[1,0,1]
	v_pk_fma_f32 v[20:21], v[156:157], v[52:53], v[20:21] op_sel_hi:[1,0,1]
	v_pk_fma_f32 v[14:15], v[154:155], v[56:57], v[14:15] op_sel_hi:[1,0,1]
	v_pk_fma_f32 v[16:17], v[156:157], v[56:57], v[16:17] op_sel_hi:[1,0,1]
	v_pk_fma_f32 v[10:11], v[154:155], v[60:61], v[10:11] op_sel_hi:[1,0,1]
	v_pk_fma_f32 v[12:13], v[156:157], v[60:61], v[12:13] op_sel_hi:[1,0,1]
	v_pk_fma_f32 v[2:3], v[154:155], v[64:65], v[2:3] op_sel_hi:[1,0,1]
	v_pk_fma_f32 v[4:5], v[156:157], v[64:65], v[4:5] op_sel_hi:[1,0,1]
	s_waitcnt vmcnt(14)
	v_pk_fma_f32 v[6:7], v[48:49], v[158:159], v[6:7] op_sel:[1,0,0]
	v_pk_fma_f32 v[8:9], v[48:49], v[160:161], v[8:9] op_sel:[1,0,0]
	v_pk_fma_f32 v[18:19], v[158:159], v[52:53], v[18:19] op_sel:[0,1,0]
	v_pk_fma_f32 v[20:21], v[160:161], v[52:53], v[20:21] op_sel:[0,1,0]
	v_pk_fma_f32 v[14:15], v[158:159], v[56:57], v[14:15] op_sel:[0,1,0]
	v_pk_fma_f32 v[16:17], v[160:161], v[56:57], v[16:17] op_sel:[0,1,0]
	v_pk_fma_f32 v[10:11], v[158:159], v[60:61], v[10:11] op_sel:[0,1,0]
	v_pk_fma_f32 v[12:13], v[160:161], v[60:61], v[12:13] op_sel:[0,1,0]
	v_pk_fma_f32 v[2:3], v[158:159], v[64:65], v[2:3] op_sel:[0,1,0]
	v_pk_fma_f32 v[4:5], v[160:161], v[64:65], v[4:5] op_sel:[0,1,0]
	s_waitcnt vmcnt(13)
	v_pk_fma_f32 v[6:7], v[50:51], v[162:163], v[6:7] op_sel_hi:[0,1,1]
	v_pk_fma_f32 v[8:9], v[50:51], v[164:165], v[8:9] op_sel_hi:[0,1,1]
	v_pk_fma_f32 v[18:19], v[162:163], v[54:55], v[18:19] op_sel_hi:[1,0,1]
	v_pk_fma_f32 v[20:21], v[164:165], v[54:55], v[20:21] op_sel_hi:[1,0,1]
	v_pk_fma_f32 v[14:15], v[162:163], v[58:59], v[14:15] op_sel_hi:[1,0,1]
	v_pk_fma_f32 v[16:17], v[164:165], v[58:59], v[16:17] op_sel_hi:[1,0,1]
	v_pk_fma_f32 v[10:11], v[162:163], v[62:63], v[10:11] op_sel_hi:[1,0,1]
	v_pk_fma_f32 v[12:13], v[164:165], v[62:63], v[12:13] op_sel_hi:[1,0,1]
	v_pk_fma_f32 v[2:3], v[162:163], v[66:67], v[2:3] op_sel_hi:[1,0,1]
	v_pk_fma_f32 v[4:5], v[164:165], v[66:67], v[4:5] op_sel_hi:[1,0,1]
	s_waitcnt vmcnt(12)
	v_pk_fma_f32 v[6:7], v[68:69], v[166:167], v[6:7] op_sel_hi:[0,1,1]
	v_pk_fma_f32 v[8:9], v[68:69], v[168:169], v[8:9] op_sel_hi:[0,1,1]
	v_pk_fma_f32 v[18:19], v[166:167], v[70:71], v[18:19] op_sel_hi:[1,0,1]
	v_pk_fma_f32 v[20:21], v[168:169], v[70:71], v[20:21] op_sel_hi:[1,0,1]
	v_pk_fma_f32 v[14:15], v[166:167], v[72:73], v[14:15] op_sel_hi:[1,0,1]
	v_pk_fma_f32 v[16:17], v[168:169], v[72:73], v[16:17] op_sel_hi:[1,0,1]
	v_pk_fma_f32 v[10:11], v[166:167], v[74:75], v[10:11] op_sel_hi:[1,0,1]
	v_pk_fma_f32 v[12:13], v[168:169], v[74:75], v[12:13] op_sel_hi:[1,0,1]
	v_pk_fma_f32 v[2:3], v[166:167], v[76:77], v[2:3] op_sel_hi:[1,0,1]
	v_pk_fma_f32 v[4:5], v[168:169], v[76:77], v[4:5] op_sel_hi:[1,0,1]
	ds_read_b128 v[48:51], v31
	ds_read_b128 v[52:55], v31 offset:4096
	ds_read_b128 v[56:59], v31 offset:8192
	ds_read_b128 v[60:63], v31 offset:12288
	ds_read_b128 v[64:67], v31 offset:16384
	s_waitcnt lgkmcnt(4)
	v_mov_b32_e32 v68, v51
	s_waitcnt lgkmcnt(3)
	v_mov_b32_e32 v70, v55
	s_waitcnt lgkmcnt(2)
	v_mov_b32_e32 v72, v59
	s_waitcnt lgkmcnt(1)
	v_mov_b32_e32 v74, v63
	s_waitcnt lgkmcnt(0)
	v_mov_b32_e32 v76, v67
	v_add_u32_e32 v31, 16, v31
	s_waitcnt vmcnt(11)
	v_pk_fma_f32 v[6:7], v[48:49], v[170:171], v[6:7] op_sel_hi:[0,1,1]
	v_pk_fma_f32 v[8:9], v[48:49], v[172:173], v[8:9] op_sel_hi:[0,1,1]
	v_pk_fma_f32 v[18:19], v[170:171], v[52:53], v[18:19] op_sel_hi:[1,0,1]
	v_pk_fma_f32 v[20:21], v[172:173], v[52:53], v[20:21] op_sel_hi:[1,0,1]
	v_pk_fma_f32 v[14:15], v[170:171], v[56:57], v[14:15] op_sel_hi:[1,0,1]
	v_pk_fma_f32 v[16:17], v[172:173], v[56:57], v[16:17] op_sel_hi:[1,0,1]
	v_pk_fma_f32 v[10:11], v[170:171], v[60:61], v[10:11] op_sel_hi:[1,0,1]
	v_pk_fma_f32 v[12:13], v[172:173], v[60:61], v[12:13] op_sel_hi:[1,0,1]
	v_pk_fma_f32 v[2:3], v[170:171], v[64:65], v[2:3] op_sel_hi:[1,0,1]
	v_pk_fma_f32 v[4:5], v[172:173], v[64:65], v[4:5] op_sel_hi:[1,0,1]
	s_waitcnt vmcnt(10)
	v_pk_fma_f32 v[6:7], v[48:49], v[174:175], v[6:7] op_sel:[1,0,0]
	v_pk_fma_f32 v[8:9], v[48:49], v[176:177], v[8:9] op_sel:[1,0,0]
	v_pk_fma_f32 v[18:19], v[174:175], v[52:53], v[18:19] op_sel:[0,1,0]
	v_pk_fma_f32 v[20:21], v[176:177], v[52:53], v[20:21] op_sel:[0,1,0]
	v_pk_fma_f32 v[14:15], v[174:175], v[56:57], v[14:15] op_sel:[0,1,0]
	v_pk_fma_f32 v[16:17], v[176:177], v[56:57], v[16:17] op_sel:[0,1,0]
	v_pk_fma_f32 v[10:11], v[174:175], v[60:61], v[10:11] op_sel:[0,1,0]
	v_pk_fma_f32 v[12:13], v[176:177], v[60:61], v[12:13] op_sel:[0,1,0]
	v_pk_fma_f32 v[2:3], v[174:175], v[64:65], v[2:3] op_sel:[0,1,0]
	v_pk_fma_f32 v[4:5], v[176:177], v[64:65], v[4:5] op_sel:[0,1,0]
	s_waitcnt vmcnt(9)
	v_pk_fma_f32 v[6:7], v[50:51], v[178:179], v[6:7] op_sel_hi:[0,1,1]
	v_pk_fma_f32 v[8:9], v[50:51], v[180:181], v[8:9] op_sel_hi:[0,1,1]
	v_pk_fma_f32 v[18:19], v[178:179], v[54:55], v[18:19] op_sel_hi:[1,0,1]
	v_pk_fma_f32 v[20:21], v[180:181], v[54:55], v[20:21] op_sel_hi:[1,0,1]
	v_pk_fma_f32 v[14:15], v[178:179], v[58:59], v[14:15] op_sel_hi:[1,0,1]
	v_pk_fma_f32 v[16:17], v[180:181], v[58:59], v[16:17] op_sel_hi:[1,0,1]
	v_pk_fma_f32 v[10:11], v[178:179], v[62:63], v[10:11] op_sel_hi:[1,0,1]
	v_pk_fma_f32 v[12:13], v[180:181], v[62:63], v[12:13] op_sel_hi:[1,0,1]
	v_pk_fma_f32 v[2:3], v[178:179], v[66:67], v[2:3] op_sel_hi:[1,0,1]
	v_pk_fma_f32 v[4:5], v[180:181], v[66:67], v[4:5] op_sel_hi:[1,0,1]
	s_waitcnt vmcnt(8)
	v_pk_fma_f32 v[6:7], v[68:69], v[182:183], v[6:7] op_sel_hi:[0,1,1]
	v_pk_fma_f32 v[8:9], v[68:69], v[184:185], v[8:9] op_sel_hi:[0,1,1]
	v_pk_fma_f32 v[18:19], v[182:183], v[70:71], v[18:19] op_sel_hi:[1,0,1]
	v_pk_fma_f32 v[20:21], v[184:185], v[70:71], v[20:21] op_sel_hi:[1,0,1]
	v_pk_fma_f32 v[14:15], v[182:183], v[72:73], v[14:15] op_sel_hi:[1,0,1]
	v_pk_fma_f32 v[16:17], v[184:185], v[72:73], v[16:17] op_sel_hi:[1,0,1]
	v_pk_fma_f32 v[10:11], v[182:183], v[74:75], v[10:11] op_sel_hi:[1,0,1]
	v_pk_fma_f32 v[12:13], v[184:185], v[74:75], v[12:13] op_sel_hi:[1,0,1]
	v_pk_fma_f32 v[2:3], v[182:183], v[76:77], v[2:3] op_sel_hi:[1,0,1]
	v_pk_fma_f32 v[4:5], v[184:185], v[76:77], v[4:5] op_sel_hi:[1,0,1]
	ds_read_b128 v[48:51], v31
	ds_read_b128 v[52:55], v31 offset:4096
	ds_read_b128 v[56:59], v31 offset:8192
	ds_read_b128 v[60:63], v31 offset:12288
	ds_read_b128 v[64:67], v31 offset:16384
	s_waitcnt lgkmcnt(4)
	v_mov_b32_e32 v68, v51
	s_waitcnt lgkmcnt(3)
	v_mov_b32_e32 v70, v55
	s_waitcnt lgkmcnt(2)
	v_mov_b32_e32 v72, v59
	s_waitcnt lgkmcnt(1)
	v_mov_b32_e32 v74, v63
	s_waitcnt lgkmcnt(0)
	v_mov_b32_e32 v76, v67
	v_add_u32_e32 v31, 16, v31
	s_waitcnt vmcnt(7)
	v_pk_fma_f32 v[6:7], v[48:49], v[186:187], v[6:7] op_sel_hi:[0,1,1]
	v_pk_fma_f32 v[8:9], v[48:49], v[188:189], v[8:9] op_sel_hi:[0,1,1]
	v_pk_fma_f32 v[18:19], v[186:187], v[52:53], v[18:19] op_sel_hi:[1,0,1]
	v_pk_fma_f32 v[20:21], v[188:189], v[52:53], v[20:21] op_sel_hi:[1,0,1]
	v_pk_fma_f32 v[14:15], v[186:187], v[56:57], v[14:15] op_sel_hi:[1,0,1]
	v_pk_fma_f32 v[16:17], v[188:189], v[56:57], v[16:17] op_sel_hi:[1,0,1]
	v_pk_fma_f32 v[10:11], v[186:187], v[60:61], v[10:11] op_sel_hi:[1,0,1]
	v_pk_fma_f32 v[12:13], v[188:189], v[60:61], v[12:13] op_sel_hi:[1,0,1]
	v_pk_fma_f32 v[2:3], v[186:187], v[64:65], v[2:3] op_sel_hi:[1,0,1]
	v_pk_fma_f32 v[4:5], v[188:189], v[64:65], v[4:5] op_sel_hi:[1,0,1]
	s_waitcnt vmcnt(6)
	v_pk_fma_f32 v[6:7], v[48:49], v[190:191], v[6:7] op_sel:[1,0,0]
	v_pk_fma_f32 v[8:9], v[48:49], v[192:193], v[8:9] op_sel:[1,0,0]
	v_pk_fma_f32 v[18:19], v[190:191], v[52:53], v[18:19] op_sel:[0,1,0]
	v_pk_fma_f32 v[20:21], v[192:193], v[52:53], v[20:21] op_sel:[0,1,0]
	v_pk_fma_f32 v[14:15], v[190:191], v[56:57], v[14:15] op_sel:[0,1,0]
	v_pk_fma_f32 v[16:17], v[192:193], v[56:57], v[16:17] op_sel:[0,1,0]
	v_pk_fma_f32 v[10:11], v[190:191], v[60:61], v[10:11] op_sel:[0,1,0]
	v_pk_fma_f32 v[12:13], v[192:193], v[60:61], v[12:13] op_sel:[0,1,0]
	v_pk_fma_f32 v[2:3], v[190:191], v[64:65], v[2:3] op_sel:[0,1,0]
	v_pk_fma_f32 v[4:5], v[192:193], v[64:65], v[4:5] op_sel:[0,1,0]
	s_waitcnt vmcnt(5)
	v_pk_fma_f32 v[6:7], v[50:51], v[194:195], v[6:7] op_sel_hi:[0,1,1]
	v_pk_fma_f32 v[8:9], v[50:51], v[196:197], v[8:9] op_sel_hi:[0,1,1]
	v_pk_fma_f32 v[18:19], v[194:195], v[54:55], v[18:19] op_sel_hi:[1,0,1]
	v_pk_fma_f32 v[20:21], v[196:197], v[54:55], v[20:21] op_sel_hi:[1,0,1]
	v_pk_fma_f32 v[14:15], v[194:195], v[58:59], v[14:15] op_sel_hi:[1,0,1]
	v_pk_fma_f32 v[16:17], v[196:197], v[58:59], v[16:17] op_sel_hi:[1,0,1]
	v_pk_fma_f32 v[10:11], v[194:195], v[62:63], v[10:11] op_sel_hi:[1,0,1]
	v_pk_fma_f32 v[12:13], v[196:197], v[62:63], v[12:13] op_sel_hi:[1,0,1]
	v_pk_fma_f32 v[2:3], v[194:195], v[66:67], v[2:3] op_sel_hi:[1,0,1]
	v_pk_fma_f32 v[4:5], v[196:197], v[66:67], v[4:5] op_sel_hi:[1,0,1]
	s_waitcnt vmcnt(4)
	v_pk_fma_f32 v[6:7], v[68:69], v[198:199], v[6:7] op_sel_hi:[0,1,1]
	v_pk_fma_f32 v[8:9], v[68:69], v[200:201], v[8:9] op_sel_hi:[0,1,1]
	v_pk_fma_f32 v[18:19], v[198:199], v[70:71], v[18:19] op_sel_hi:[1,0,1]
	v_pk_fma_f32 v[20:21], v[200:201], v[70:71], v[20:21] op_sel_hi:[1,0,1]
	v_pk_fma_f32 v[14:15], v[198:199], v[72:73], v[14:15] op_sel_hi:[1,0,1]
	v_pk_fma_f32 v[16:17], v[200:201], v[72:73], v[16:17] op_sel_hi:[1,0,1]
	v_pk_fma_f32 v[10:11], v[198:199], v[74:75], v[10:11] op_sel_hi:[1,0,1]
	v_pk_fma_f32 v[12:13], v[200:201], v[74:75], v[12:13] op_sel_hi:[1,0,1]
	v_pk_fma_f32 v[2:3], v[198:199], v[76:77], v[2:3] op_sel_hi:[1,0,1]
	v_pk_fma_f32 v[4:5], v[200:201], v[76:77], v[4:5] op_sel_hi:[1,0,1]
	ds_read_b128 v[48:51], v31
	ds_read_b128 v[52:55], v31 offset:4096
	ds_read_b128 v[56:59], v31 offset:8192
	ds_read_b128 v[60:63], v31 offset:12288
	ds_read_b128 v[64:67], v31 offset:16384
	s_waitcnt lgkmcnt(4)
	v_mov_b32_e32 v68, v51
	s_waitcnt lgkmcnt(3)
	v_mov_b32_e32 v70, v55
	s_waitcnt lgkmcnt(2)
	v_mov_b32_e32 v72, v59
	s_waitcnt lgkmcnt(1)
	v_mov_b32_e32 v74, v63
	s_waitcnt lgkmcnt(0)
	v_mov_b32_e32 v76, v67
	v_add_u32_e32 v31, 16, v31
	s_waitcnt vmcnt(3)
	v_pk_fma_f32 v[6:7], v[48:49], v[206:207], v[6:7] op_sel_hi:[0,1,1]
	v_pk_fma_f32 v[8:9], v[48:49], v[208:209], v[8:9] op_sel_hi:[0,1,1]
	v_pk_fma_f32 v[18:19], v[206:207], v[52:53], v[18:19] op_sel_hi:[1,0,1]
	v_pk_fma_f32 v[20:21], v[208:209], v[52:53], v[20:21] op_sel_hi:[1,0,1]
	v_pk_fma_f32 v[14:15], v[206:207], v[56:57], v[14:15] op_sel_hi:[1,0,1]
	v_pk_fma_f32 v[16:17], v[208:209], v[56:57], v[16:17] op_sel_hi:[1,0,1]
	v_pk_fma_f32 v[10:11], v[206:207], v[60:61], v[10:11] op_sel_hi:[1,0,1]
	v_pk_fma_f32 v[12:13], v[208:209], v[60:61], v[12:13] op_sel_hi:[1,0,1]
	v_pk_fma_f32 v[2:3], v[206:207], v[64:65], v[2:3] op_sel_hi:[1,0,1]
	v_pk_fma_f32 v[4:5], v[208:209], v[64:65], v[4:5] op_sel_hi:[1,0,1]
	s_waitcnt vmcnt(2)
	v_pk_fma_f32 v[6:7], v[48:49], v[210:211], v[6:7] op_sel:[1,0,0]
	v_pk_fma_f32 v[8:9], v[48:49], v[212:213], v[8:9] op_sel:[1,0,0]
	v_pk_fma_f32 v[18:19], v[210:211], v[52:53], v[18:19] op_sel:[0,1,0]
	v_pk_fma_f32 v[20:21], v[212:213], v[52:53], v[20:21] op_sel:[0,1,0]
	v_pk_fma_f32 v[14:15], v[210:211], v[56:57], v[14:15] op_sel:[0,1,0]
	v_pk_fma_f32 v[16:17], v[212:213], v[56:57], v[16:17] op_sel:[0,1,0]
	v_pk_fma_f32 v[10:11], v[210:211], v[60:61], v[10:11] op_sel:[0,1,0]
	v_pk_fma_f32 v[12:13], v[212:213], v[60:61], v[12:13] op_sel:[0,1,0]
	v_pk_fma_f32 v[2:3], v[210:211], v[64:65], v[2:3] op_sel:[0,1,0]
	v_pk_fma_f32 v[4:5], v[212:213], v[64:65], v[4:5] op_sel:[0,1,0]
	s_waitcnt vmcnt(1)
	v_pk_fma_f32 v[6:7], v[50:51], v[214:215], v[6:7] op_sel_hi:[0,1,1]
	v_pk_fma_f32 v[8:9], v[50:51], v[216:217], v[8:9] op_sel_hi:[0,1,1]
	v_pk_fma_f32 v[18:19], v[214:215], v[54:55], v[18:19] op_sel_hi:[1,0,1]
	v_pk_fma_f32 v[20:21], v[216:217], v[54:55], v[20:21] op_sel_hi:[1,0,1]
	v_pk_fma_f32 v[14:15], v[214:215], v[58:59], v[14:15] op_sel_hi:[1,0,1]
	v_pk_fma_f32 v[16:17], v[216:217], v[58:59], v[16:17] op_sel_hi:[1,0,1]
	v_pk_fma_f32 v[10:11], v[214:215], v[62:63], v[10:11] op_sel_hi:[1,0,1]
	v_pk_fma_f32 v[12:13], v[216:217], v[62:63], v[12:13] op_sel_hi:[1,0,1]
	v_pk_fma_f32 v[2:3], v[214:215], v[66:67], v[2:3] op_sel_hi:[1,0,1]
	v_pk_fma_f32 v[4:5], v[216:217], v[66:67], v[4:5] op_sel_hi:[1,0,1]
	s_waitcnt vmcnt(0)
	v_pk_fma_f32 v[6:7], v[68:69], v[218:219], v[6:7] op_sel_hi:[0,1,1]
	v_pk_fma_f32 v[8:9], v[68:69], v[220:221], v[8:9] op_sel_hi:[0,1,1]
	v_pk_fma_f32 v[18:19], v[218:219], v[70:71], v[18:19] op_sel_hi:[1,0,1]
	v_pk_fma_f32 v[20:21], v[220:221], v[70:71], v[20:21] op_sel_hi:[1,0,1]
	v_pk_fma_f32 v[14:15], v[218:219], v[72:73], v[14:15] op_sel_hi:[1,0,1]
	v_pk_fma_f32 v[16:17], v[220:221], v[72:73], v[16:17] op_sel_hi:[1,0,1]
	v_pk_fma_f32 v[10:11], v[218:219], v[74:75], v[10:11] op_sel_hi:[1,0,1]
	v_pk_fma_f32 v[12:13], v[220:221], v[74:75], v[12:13] op_sel_hi:[1,0,1]
	v_pk_fma_f32 v[2:3], v[218:219], v[76:77], v[2:3] op_sel_hi:[1,0,1]
	v_pk_fma_f32 v[4:5], v[220:221], v[76:77], v[4:5] op_sel_hi:[1,0,1]
	ds_write_b128 v30, v[6:9] offset:20480
	ds_write_b128 v30, v[18:21] offset:20608
	ds_write_b128 v30, v[14:17] offset:20736
	ds_write_b128 v30, v[10:13] offset:20864
	ds_write_b128 v30, v[2:5] offset:20992
	s_waitcnt lgkmcnt(0)
	s_barrier
	s_and_saveexec_b64 s[4:5], vcc
	s_cbranch_execz .LBB0_17
	v_add_u32_e32 v2, 0x5000, v28
	ds_read2_b32 v[2:3], v2 offset1:160
	v_add_u32_e32 v4, 0x5400, v28
	ds_read2_b32 v[4:5], v4 offset0:64 offset1:224
	v_add_u32_e32 v6, 0x5a00, v28
	ds_read2_b32 v[6:7], v6 offset1:160
	s_waitcnt lgkmcnt(2)
	v_add_f32_e32 v2, 0, v2
	v_add_f32_e32 v2, v2, v3
	s_waitcnt lgkmcnt(1)
	v_add_f32_e32 v2, v2, v4
	v_add_f32_e32 v8, v2, v5
	v_add_u32_e32 v2, 0x5e00, v28
	ds_read2_b32 v[2:3], v2 offset0:64 offset1:224
	v_add_u32_e32 v4, 0x6400, v28
	ds_read2_b32 v[4:5], v4 offset1:160
	s_waitcnt lgkmcnt(2)
	v_add_f32_e32 v6, v8, v6
	v_add_f32_e32 v6, v6, v7
	s_waitcnt lgkmcnt(1)
	v_add_f32_e32 v2, v6, v2
	v_add_f32_e32 v2, v2, v3
	s_waitcnt lgkmcnt(0)
	v_add_f32_e32 v2, v2, v4
	v_add_f32_e32 v8, v2, v5
	v_add_u32_e32 v2, 0x6800, v28
	ds_read2_b32 v[2:3], v2 offset0:64 offset1:224
	v_add_u32_e32 v4, 0x6e00, v28
	ds_read2_b32 v[4:5], v4 offset1:160
	v_add_u32_e32 v6, 0x7200, v28
	ds_read2_b32 v[6:7], v6 offset0:64 offset1:224
	s_waitcnt lgkmcnt(2)
	v_add_f32_e32 v2, v8, v2
	v_add_f32_e32 v2, v2, v3
	s_waitcnt lgkmcnt(1)
	v_add_f32_e32 v2, v2, v4
	v_add_f32_e32 v2, v2, v5
	s_waitcnt lgkmcnt(0)
	v_add_f32_e32 v2, v2, v6
	v_add_f32_e32 v8, v2, v7
	v_add_u32_e32 v2, 0x7800, v28
	ds_read2_b32 v[2:3], v2 offset1:160
	v_add_u32_e32 v4, 0x7c00, v28
	ds_read2_b32 v[4:5], v4 offset0:64 offset1:224
	v_add_u32_e32 v6, 0x8200, v28
	ds_read2_b32 v[6:7], v6 offset1:160
	s_waitcnt lgkmcnt(2)
	v_add_f32_e32 v2, v8, v2
	v_add_f32_e32 v2, v2, v3
	s_waitcnt lgkmcnt(1)
	v_add_f32_e32 v2, v2, v4
	v_add_f32_e32 v2, v2, v5
	s_waitcnt lgkmcnt(0)
	v_add_f32_e32 v2, v2, v6
	v_or_b32_e32 v6, s10, v1
	s_mul_i32 s10, s18, 0x1800
	v_add_u32_e32 v8, s10, v6
	v_ashrrev_i32_e32 v9, 31, v8
	v_lshl_add_u64 v[8:9], v[8:9], 2, s[6:7]
	global_load_dword v11, v[8:9], off
	v_add_f32_e32 v7, v2, v7
	v_add_u32_e32 v2, 0x8600, v28
	ds_read2_b32 v[2:3], v2 offset0:64 offset1:224
	v_add_u32_e32 v4, 0x8c00, v28
	ds_read2_b32 v[4:5], v4 offset1:160
	v_add_u32_e32 v10, 0x9000, v28
	ds_read2_b32 v[8:9], v10 offset0:64 offset1:224
	s_waitcnt lgkmcnt(2)
	v_add_f32_e32 v2, v7, v2
	v_add_f32_e32 v2, v2, v3
	s_waitcnt lgkmcnt(1)
	v_add_f32_e32 v2, v2, v4
	v_add_f32_e32 v2, v2, v5
	s_waitcnt lgkmcnt(0)
	v_add_f32_e32 v2, v2, v8
	v_add_f32_e32 v7, v2, v9
	v_add_u32_e32 v2, 0x9600, v28
	ds_read2_b32 v[2:3], v2 offset1:160
	v_add_u32_e32 v4, 0x9a00, v28
	ds_read2_b32 v[4:5], v4 offset0:64 offset1:224
	v_add_u32_e32 v8, 0xa000, v28
	ds_read2_b32 v[8:9], v8 offset1:160
	s_waitcnt lgkmcnt(2)
	v_add_f32_e32 v2, v7, v2
	v_add_f32_e32 v2, v2, v3
	s_waitcnt lgkmcnt(1)
	v_add_f32_e32 v2, v2, v4
	v_add_f32_e32 v2, v2, v5
	s_waitcnt lgkmcnt(0)
	v_add_f32_e32 v2, v2, v8
	v_add_f32_e32 v7, v2, v9
	v_add_u32_e32 v2, 0xa400, v28
	ds_read2_b32 v[2:3], v2 offset0:64 offset1:224
	v_add_u32_e32 v4, 0xaa00, v28
	ds_read2_b32 v[4:5], v4 offset1:160
	v_add_u32_e32 v8, 0xae00, v28
	ds_read2_b32 v[8:9], v8 offset0:64 offset1:224
	s_waitcnt lgkmcnt(2)
	v_add_f32_e32 v2, v7, v2
	v_add_f32_e32 v2, v2, v3
	s_waitcnt lgkmcnt(1)
	v_add_f32_e32 v2, v2, v4
	v_add_f32_e32 v2, v2, v5
	s_waitcnt lgkmcnt(0)
	v_add_f32_e32 v2, v2, v8
	v_add_f32_e32 v7, v2, v9
	v_add_u32_e32 v2, 0xb400, v28
	ds_read2_b32 v[2:3], v2 offset1:160
	v_add_u32_e32 v4, 0xb800, v28
	ds_read2_b32 v[4:5], v4 offset0:64 offset1:224
	v_add_u32_e32 v8, 0xbe00, v28
	ds_read2_b32 v[8:9], v8 offset1:160
	s_waitcnt lgkmcnt(2)
	v_add_f32_e32 v2, v7, v2
	v_add_f32_e32 v2, v2, v3
	s_waitcnt lgkmcnt(1)
	v_add_f32_e32 v2, v2, v4
	v_add_f32_e32 v2, v2, v5
	s_waitcnt lgkmcnt(0)
	v_add_f32_e32 v2, v2, v8
	v_add_f32_e32 v7, v2, v9
	v_add_u32_e32 v2, 0xc200, v28
	ds_read2_b32 v[2:3], v2 offset0:64 offset1:224
	v_add_u32_e32 v4, 0xc800, v28
	ds_read2_b32 v[4:5], v4 offset1:160
	v_add_u32_e32 v8, 0xcc00, v28
	ds_read2_b32 v[8:9], v8 offset0:64 offset1:224
	s_waitcnt lgkmcnt(2)
	v_add_f32_e32 v2, v7, v2
	v_add_f32_e32 v2, v2, v3
	s_waitcnt lgkmcnt(1)
	v_add_f32_e32 v2, v2, v4
	v_add_f32_e32 v2, v2, v5
	s_waitcnt lgkmcnt(0)
	v_add_f32_e32 v2, v2, v8
	v_add_f32_e32 v7, v2, v9
	v_add_u32_e32 v2, 0xd200, v28
	ds_read2_b32 v[2:3], v2 offset1:160
	v_add_u32_e32 v4, 0xd600, v28
	ds_read2_b32 v[4:5], v4 offset0:64 offset1:224
	v_add_u32_e32 v8, 0xdc00, v28
	ds_read2_b32 v[8:9], v8 offset1:160
	s_waitcnt lgkmcnt(2)
	v_add_f32_e32 v2, v7, v2
	v_add_f32_e32 v2, v2, v3
	s_waitcnt lgkmcnt(1)
	v_add_f32_e32 v2, v2, v4
	v_add_f32_e32 v2, v2, v5
	s_waitcnt lgkmcnt(0)
	v_add_f32_e32 v2, v2, v8
	v_add_f32_e32 v7, v2, v9
	v_add_u32_e32 v2, 0xe000, v28
	ds_read2_b32 v[2:3], v2 offset0:64 offset1:224
	v_add_u32_e32 v4, 0xe600, v28
	ds_read2_b32 v[4:5], v4 offset1:160
	v_add_u32_e32 v8, 0xea00, v28
	ds_read2_b32 v[8:9], v8 offset0:64 offset1:224
	s_waitcnt lgkmcnt(2)
	v_add_f32_e32 v2, v7, v2
	v_add_f32_e32 v2, v2, v3
	s_waitcnt lgkmcnt(1)
	v_add_f32_e32 v2, v2, v4
	v_add_f32_e32 v2, v2, v5
	s_waitcnt lgkmcnt(0)
	v_add_f32_e32 v2, v2, v8
	v_add_f32_e32 v2, v2, v9
	s_waitcnt vmcnt(0)
	v_add_f32_e32 v8, v2, v11
	v_mad_i64_i32 v[2:3], s[10:11], s18, 5, v[22:23]
	v_mov_b64_e32 v[4:5], s[8:9]
	v_mad_u64_u32 v[4:5], s[10:11], v2, s14, v[4:5]
	v_ashrrev_i32_e32 v7, 31, v6
	v_mad_i32_i24 v5, v3, s14, v5
	v_lshl_add_u64 v[2:3], v[6:7], 2, v[4:5]
	global_store_dword v[2:3], v8, off
	s_branch .LBB0_17
